# split-phase barrier: the 16 sample WGs arrive at the in-proj->mixer grid barrier but do not wait there (sample GEMM needs nothing from that phase); wait made up in the 16-WG sub-barrier
# speedup vs baseline: 1.0124x; 1.0124x over previous
.LBB0_152:
	s_waitcnt vmcnt(0)
	v_cndmask_b32_e64 v0, 0, 1, s[4:5]
	v_cmp_ne_u32_e64 s[0:1], 1, v0
	s_andn2_b64 vcc, exec, s[4:5]
	s_waitcnt lgkmcnt(0)
	v_writelane_b32 v235, s0, 41
	s_barrier
	s_mov_b32 s100, -1
	s_nop 0
	v_writelane_b32 v235, s1, 42
	s_cbranch_vccnz .LBB0_206
	v_mbcnt_lo_u32_b32 v0, -1, 0
	v_mbcnt_hi_u32_b32 v0, -1, v0
	s_nop 0
	v_cmp_eq_u32_e32 vcc, 0, v0
	s_and_saveexec_b64 s[0:1], vcc
	s_cbranch_execz .LBB0_205
	s_add_i32 s4, 0, 0x20000
	v_mov_b32_e32 v0, s4
	s_waitcnt vmcnt(0) expcnt(0) lgkmcnt(0)
	ds_read_b32 v2, v0
	s_add_i32 s4, 0, 0x20004
	v_mov_b32_e32 v0, s4
	ds_read_b32 v0, v0
	s_waitcnt lgkmcnt(1)
	v_cmp_ne_u32_e32 vcc, 0, v2
	s_cbranch_vccnz .LBB0_169
	v_readlane_b32 s4, v235, 0
	v_readlane_b32 s5, v235, 1
	v_readlane_b32 s6, v235, 2
	s_mul_i32 s18, s5, s6
	s_mul_i32 s18, s18, s4
	s_add_u32 s4, s78, 0x1000
	s_addc_u32 s5, s79, 0
	s_add_u32 s6, s78, 0x1100
	s_addc_u32 s7, s79, 0
	s_add_u32 s8, s78, 0x1200
	s_addc_u32 s9, s79, 0
	s_add_u32 s10, s78, 0x1300
	s_addc_u32 s11, s79, 0
	s_mov_b32 s19, 1
	v_mov_b32_e32 v16, 0
	s_branch .LBB0_157

.LBB0_171:
	s_or_b64 exec, exec, s[8:9]
	v_cvt_f32_u32_e32 v4, v2
	s_waitcnt vmcnt(0)
	v_readfirstlane_b32 s6, v3
	v_sub_u32_e32 v3, 0, v2
	v_rcp_iflag_f32_e32 v4, v4
	v_add_u32_e32 v5, s6, v1
	v_mul_f32_e32 v4, 0x4f7ffffe, v4
	v_cvt_u32_f32_e32 v4, v4
	v_mul_lo_u32 v1, v3, v4
	v_mul_hi_u32 v1, v4, v1
	v_add_u32_e32 v1, v4, v1
	v_mul_hi_u32 v1, v5, v1
	v_mul_lo_u32 v3, v1, v2
	v_sub_u32_e32 v3, v5, v3
	v_add_u32_e32 v4, 1, v1
	v_cmp_ge_u32_e32 vcc, v3, v2
	s_nop 1
	v_cndmask_b32_e32 v1, v1, v4, vcc
	v_sub_u32_e32 v4, v3, v2
	v_cndmask_b32_e32 v3, v3, v4, vcc
	v_add_u32_e32 v4, 1, v1
	v_cmp_ge_u32_e32 vcc, v3, v2
	v_add_u32_e32 v3, 1, v5
	s_nop 0
	v_cndmask_b32_e32 v1, v1, v4, vcc
	v_mul_lo_u32 v4, v2, v1
	v_add_u32_e32 v2, v4, v2
	v_cmp_ne_u32_e32 vcc, v3, v2
	s_and_saveexec_b64 s[6:7], vcc
	s_xor_b64 s[6:7], exec, s[6:7]
	s_cbranch_execz .LBB0_185
	s_waitcnt lgkmcnt(0)
	v_mov_b32_e32 v0, 0x3500
	global_load_dword v0, v0, s[78:79] sc1
	s_add_u32 s10, s78, 0x3500
	s_addc_u32 s11, s79, 0
	s_waitcnt vmcnt(0)
	v_cmp_eq_u32_e32 vcc, v0, v1
	s_cmp_lt_u32 s2, 16
	s_cbranch_scc0 ATB0_3866
	v_readfirstlane_b32 s100, v1
	s_mov_b64 vcc, 0
ATB0_3866:
	s_and_saveexec_b64 s[8:9], vcc
	s_cbranch_execz .LBB0_184
	s_mov_b32 s22, 1
	s_mov_b64 s[12:13], 0
	v_mov_b32_e32 v0, 0
	s_branch .LBB0_175

.LBB0_188:
	s_or_b64 exec, exec, s[8:9]
	v_cvt_f32_u32_e32 v3, v0
	s_waitcnt vmcnt(0)
	v_readfirstlane_b32 s6, v2
	s_add_u32 s8, s78, 0x3500
	s_addc_u32 s9, s79, 0
	v_rcp_iflag_f32_e32 v3, v3
	v_add_u32_e32 v1, s6, v1
	v_add_u32_e32 v4, 1, v1
	s_mov_b64 s[10:11], -1
	v_mul_f32_e32 v2, 0x4f7ffffe, v3
	v_cvt_u32_f32_e32 v2, v2
	v_sub_u32_e32 v3, 0, v0
	v_mul_lo_u32 v3, v3, v2
	v_mul_hi_u32 v3, v2, v3
	v_add_u32_e32 v2, v2, v3
	v_mul_hi_u32 v2, v1, v2
	v_mul_lo_u32 v3, v2, v0
	v_sub_u32_e32 v1, v1, v3
	v_add_u32_e32 v5, 1, v2
	v_cmp_ge_u32_e32 vcc, v1, v0
	v_sub_u32_e32 v3, v1, v0
	s_nop 0
	v_cndmask_b32_e32 v2, v2, v5, vcc
	v_cndmask_b32_e32 v1, v1, v3, vcc
	v_add_u32_e32 v3, 1, v2
	v_cmp_ge_u32_e32 vcc, v1, v0
	s_nop 1
	v_cndmask_b32_e32 v2, v2, v3, vcc
	v_mul_lo_u32 v1, v0, v2
	v_add_u32_e32 v0, v1, v0
	v_cmp_ne_u32_e32 vcc, v4, v0
	v_mov_b64_e32 v[0:1], s[8:9]
	s_and_saveexec_b64 s[6:7], vcc
	s_cbranch_execz .LBB0_200
	v_mov_b32_e32 v0, 0
	global_load_dword v1, v0, s[8:9] sc1
	s_mov_b64 s[14:15], 0
	s_waitcnt vmcnt(0)
	v_cmp_eq_u32_e32 vcc, v1, v2
	s_cmp_lt_u32 s2, 16
	s_cbranch_scc0 ATB0_4007
	v_readfirstlane_b32 s100, v2
	s_mov_b64 vcc, 0
ATB0_4007:
	s_and_saveexec_b64 s[12:13], vcc
	s_cbranch_execz .LBB0_199
	s_add_u32 s10, s78, 0x200
	s_addc_u32 s11, s79, 0
	s_mov_b32 s26, 1
	s_branch .LBB0_192

.LBB0_213:
	v_lshl_add_u32 v128, s4, 8, v141
	v_ashrrev_i32_e32 v129, 31, v128
	v_lshl_add_u64 v[130:131], v[128:129], 2, s[88:89]
	global_load_dword v136, v[130:131], off
	global_load_dword v236, v[130:131], off offset:64
	global_load_dword v237, v[130:131], off offset:128
	global_load_dword v238, v[130:131], off offset:192
	global_load_dword v239, v[130:131], off offset:512
	global_load_dword v240, v[130:131], off offset:576
	global_load_dword v241, v[130:131], off offset:640
	global_load_dword v242, v[130:131], off offset:704
	v_ashrrev_i32_e32 v129, 1, v140
	s_lshl_b32 s1, s0, 8
	v_readlane_b32 s4, v235, 37
	v_and_b32_e32 v129, -8, v129
	s_or_b32 s1, s4, s1
	v_add_u32_e32 v134, s1, v129
	s_movk_i32 s0, 0x1040
	v_mov_b64_e32 v[132:133], s[52:53]
	v_ashrrev_i32_e32 v135, 31, v134
	v_mad_i64_i32 v[138:139], s[4:5], v128, s0, v[132:133]
	v_or_b32_e32 v140, 16, v128
	v_lshlrev_b64 v[134:135], 1, v[134:135]
	v_ashrrev_i32_e32 v141, 31, v140
	v_lshl_add_u64 v[138:139], v[138:139], 0, v[134:135]
	v_lshl_add_u64 v[142:143], v[140:141], 2, s[88:89]
	s_movk_i32 s1, 0x80
	v_writelane_b32 v235, s1, 45
	s_waitcnt vmcnt(0)
	v_pk_mul_f32 v[126:127], v[126:127], v[136:137] op_sel_hi:[1,0]
	v_pk_mul_f32 v[124:125], v[124:125], v[136:137] op_sel_hi:[1,0]
	v_pk_mul_f32 v[122:123], v[122:123], v[136:137] op_sel_hi:[1,0]
	v_pk_mul_f32 v[120:121], v[120:121], v[136:137] op_sel_hi:[1,0]
	v_pk_mul_f32 v[118:119], v[118:119], v[136:137] op_sel_hi:[1,0]
	v_pk_mul_f32 v[116:117], v[116:117], v[136:137] op_sel_hi:[1,0]
	v_pk_mul_f32 v[144:145], v[114:115], v[136:137] op_sel_hi:[1,0]
	v_pk_mul_f32 v[136:137], v[112:113], v[136:137] op_sel_hi:[1,0]
	v_cvt_pk_bf16_f32 v112, v124, v125
	v_cvt_pk_bf16_f32 v113, v126, v127
	v_cvt_pk_bf16_f32 v114, v120, v121
	v_cvt_pk_bf16_f32 v115, v122, v123
	global_store_dwordx4 v[138:139], v[112:115], off
	s_nop 1
	v_cvt_pk_bf16_f32 v112, v116, v117
	v_cvt_pk_bf16_f32 v113, v118, v119
	v_cvt_pk_bf16_f32 v114, v136, v137
	v_cvt_pk_bf16_f32 v115, v144, v145
	global_store_dwordx4 v[138:139], v[112:115], off offset:256
	s_nop 1
	v_mad_i64_i32 v[116:117], s[4:5], v140, s0, v[132:133]
	v_or_b32_e32 v114, 32, v128
	v_ashrrev_i32_e32 v115, 31, v114
	v_lshl_add_u64 v[116:117], v[116:117], 0, v[134:135]
	v_lshl_add_u64 v[118:119], v[114:115], 2, s[88:89]
	s_nop 1
	v_mov_b32_e32 v112, v236
	v_pk_mul_f32 v[110:111], v[110:111], v[112:113] op_sel_hi:[1,0]
	v_pk_mul_f32 v[108:109], v[108:109], v[112:113] op_sel_hi:[1,0]
	v_pk_mul_f32 v[106:107], v[106:107], v[112:113] op_sel_hi:[1,0]
	v_pk_mul_f32 v[104:105], v[104:105], v[112:113] op_sel_hi:[1,0]
	v_pk_mul_f32 v[102:103], v[102:103], v[112:113] op_sel_hi:[1,0]
	v_pk_mul_f32 v[100:101], v[100:101], v[112:113] op_sel_hi:[1,0]
	v_pk_mul_f32 v[120:121], v[98:99], v[112:113] op_sel_hi:[1,0]
	v_pk_mul_f32 v[112:113], v[96:97], v[112:113] op_sel_hi:[1,0]
	v_cvt_pk_bf16_f32 v96, v108, v109
	v_cvt_pk_bf16_f32 v97, v110, v111
	v_cvt_pk_bf16_f32 v98, v104, v105
	v_cvt_pk_bf16_f32 v99, v106, v107
	global_store_dwordx4 v[116:117], v[96:99], off
	s_nop 1
	v_cvt_pk_bf16_f32 v96, v100, v101
	v_cvt_pk_bf16_f32 v97, v102, v103
	v_cvt_pk_bf16_f32 v98, v112, v113
	v_cvt_pk_bf16_f32 v99, v120, v121
	global_store_dwordx4 v[116:117], v[96:99], off offset:256
	s_nop 1
	v_mad_i64_i32 v[100:101], s[4:5], v114, s0, v[132:133]
	v_or_b32_e32 v98, 48, v128
	v_ashrrev_i32_e32 v99, 31, v98
	v_lshl_add_u64 v[100:101], v[100:101], 0, v[134:135]
	v_lshl_add_u64 v[102:103], v[98:99], 2, s[88:89]
	s_nop 1
	v_mov_b32_e32 v96, v237
	v_pk_mul_f32 v[94:95], v[94:95], v[96:97] op_sel_hi:[1,0]
	v_pk_mul_f32 v[92:93], v[92:93], v[96:97] op_sel_hi:[1,0]
	v_pk_mul_f32 v[90:91], v[90:91], v[96:97] op_sel_hi:[1,0]
	v_pk_mul_f32 v[88:89], v[88:89], v[96:97] op_sel_hi:[1,0]
	v_pk_mul_f32 v[82:83], v[82:83], v[96:97] op_sel_hi:[1,0]
	v_pk_mul_f32 v[80:81], v[80:81], v[96:97] op_sel_hi:[1,0]
	v_pk_mul_f32 v[104:105], v[74:75], v[96:97] op_sel_hi:[1,0]
	v_pk_mul_f32 v[96:97], v[72:73], v[96:97] op_sel_hi:[1,0]
	v_cvt_pk_bf16_f32 v72, v92, v93
	v_cvt_pk_bf16_f32 v73, v94, v95
	v_cvt_pk_bf16_f32 v74, v88, v89
	v_cvt_pk_bf16_f32 v75, v90, v91
	global_store_dwordx4 v[100:101], v[72:75], off
	s_nop 1
	v_cvt_pk_bf16_f32 v72, v80, v81
	v_cvt_pk_bf16_f32 v73, v82, v83
	v_cvt_pk_bf16_f32 v74, v96, v97
	v_cvt_pk_bf16_f32 v75, v104, v105
	global_store_dwordx4 v[100:101], v[72:75], off offset:256
	s_nop 1
	s_nop 1
	v_mov_b32_e32 v72, v238
	v_pk_mul_f32 v[80:81], v[86:87], v[72:73] op_sel_hi:[1,0]
	v_mad_i64_i32 v[74:75], s[4:5], v98, s0, v[132:133]
	v_lshl_add_u64 v[74:75], v[74:75], 0, v[134:135]
	v_pk_mul_f32 v[82:83], v[84:85], v[72:73] op_sel_hi:[1,0]
	v_pk_mul_f32 v[78:79], v[78:79], v[72:73] op_sel_hi:[1,0]
	v_pk_mul_f32 v[76:77], v[76:77], v[72:73] op_sel_hi:[1,0]
	v_pk_mul_f32 v[70:71], v[70:71], v[72:73] op_sel_hi:[1,0]
	v_pk_mul_f32 v[68:69], v[68:69], v[72:73] op_sel_hi:[1,0]
	v_pk_mul_f32 v[84:85], v[66:67], v[72:73] op_sel_hi:[1,0]
	v_pk_mul_f32 v[72:73], v[64:65], v[72:73] op_sel_hi:[1,0]
	v_cvt_pk_bf16_f32 v64, v82, v83
	v_cvt_pk_bf16_f32 v65, v80, v81
	v_cvt_pk_bf16_f32 v66, v76, v77
	v_cvt_pk_bf16_f32 v67, v78, v79
	global_store_dwordx4 v[74:75], v[64:67], off
	s_nop 1
	v_cvt_pk_bf16_f32 v64, v68, v69
	v_cvt_pk_bf16_f32 v65, v70, v71
	v_cvt_pk_bf16_f32 v66, v72, v73
	v_cvt_pk_bf16_f32 v67, v84, v85
	global_store_dwordx4 v[74:75], v[64:67], off offset:256
	s_nop 1
	s_nop 0
	v_add_u32_e32 v65, 0x80, v128
	v_mad_i64_i32 v[66:67], s[4:5], v65, s0, v[132:133]
	v_lshl_add_u64 v[66:67], v[66:67], 0, v[134:135]
	s_nop 1
	v_mov_b32_e32 v64, v239
	v_pk_mul_f32 v[62:63], v[62:63], v[64:65] op_sel_hi:[1,0]
	v_pk_mul_f32 v[60:61], v[60:61], v[64:65] op_sel_hi:[1,0]
	v_pk_mul_f32 v[58:59], v[58:59], v[64:65] op_sel_hi:[1,0]
	v_pk_mul_f32 v[56:57], v[56:57], v[64:65] op_sel_hi:[1,0]
	v_pk_mul_f32 v[54:55], v[54:55], v[64:65] op_sel_hi:[1,0]
	v_pk_mul_f32 v[52:53], v[52:53], v[64:65] op_sel_hi:[1,0]
	v_pk_mul_f32 v[68:69], v[50:51], v[64:65] op_sel_hi:[1,0]
	v_pk_mul_f32 v[64:65], v[48:49], v[64:65] op_sel_hi:[1,0]
	v_cvt_pk_bf16_f32 v48, v60, v61
	v_cvt_pk_bf16_f32 v49, v62, v63
	v_cvt_pk_bf16_f32 v50, v56, v57
	v_cvt_pk_bf16_f32 v51, v58, v59
	global_store_dwordx4 v[66:67], v[48:51], off
	s_nop 1
	v_cvt_pk_bf16_f32 v48, v52, v53
	v_cvt_pk_bf16_f32 v49, v54, v55
	v_cvt_pk_bf16_f32 v50, v64, v65
	v_cvt_pk_bf16_f32 v51, v68, v69
	global_store_dwordx4 v[66:67], v[48:51], off offset:256
	s_nop 1
	s_nop 0
	v_add_u32_e32 v49, 0x90, v128
	v_mad_i64_i32 v[50:51], s[4:5], v49, s0, v[132:133]
	v_lshl_add_u64 v[50:51], v[50:51], 0, v[134:135]
	s_nop 1
	v_mov_b32_e32 v48, v240
	v_pk_mul_f32 v[46:47], v[46:47], v[48:49] op_sel_hi:[1,0]
	v_pk_mul_f32 v[44:45], v[44:45], v[48:49] op_sel_hi:[1,0]
	v_pk_mul_f32 v[42:43], v[42:43], v[48:49] op_sel_hi:[1,0]
	v_pk_mul_f32 v[40:41], v[40:41], v[48:49] op_sel_hi:[1,0]
	v_pk_mul_f32 v[38:39], v[38:39], v[48:49] op_sel_hi:[1,0]
	v_pk_mul_f32 v[36:37], v[36:37], v[48:49] op_sel_hi:[1,0]
	v_pk_mul_f32 v[52:53], v[34:35], v[48:49] op_sel_hi:[1,0]
	v_pk_mul_f32 v[48:49], v[32:33], v[48:49] op_sel_hi:[1,0]
	v_cvt_pk_bf16_f32 v32, v44, v45
	v_cvt_pk_bf16_f32 v33, v46, v47
	v_cvt_pk_bf16_f32 v34, v40, v41
	v_cvt_pk_bf16_f32 v35, v42, v43
	global_store_dwordx4 v[50:51], v[32:35], off
	s_nop 1
	v_cvt_pk_bf16_f32 v32, v36, v37
	v_cvt_pk_bf16_f32 v33, v38, v39
	v_cvt_pk_bf16_f32 v34, v48, v49
	v_cvt_pk_bf16_f32 v35, v52, v53
	global_store_dwordx4 v[50:51], v[32:35], off offset:256
	s_nop 1
	s_nop 0
	v_add_u32_e32 v33, 0xa0, v128
	v_mad_i64_i32 v[34:35], s[4:5], v33, s0, v[132:133]
	v_lshl_add_u64 v[34:35], v[34:35], 0, v[134:135]
	s_nop 1
	v_mov_b32_e32 v32, v241
	v_pk_mul_f32 v[30:31], v[30:31], v[32:33] op_sel_hi:[1,0]
	v_pk_mul_f32 v[28:29], v[28:29], v[32:33] op_sel_hi:[1,0]
	v_pk_mul_f32 v[26:27], v[26:27], v[32:33] op_sel_hi:[1,0]
	v_pk_mul_f32 v[24:25], v[24:25], v[32:33] op_sel_hi:[1,0]
	v_pk_mul_f32 v[22:23], v[22:23], v[32:33] op_sel_hi:[1,0]
	v_pk_mul_f32 v[20:21], v[20:21], v[32:33] op_sel_hi:[1,0]
	v_pk_mul_f32 v[36:37], v[18:19], v[32:33] op_sel_hi:[1,0]
	v_pk_mul_f32 v[32:33], v[16:17], v[32:33] op_sel_hi:[1,0]
	v_cvt_pk_bf16_f32 v16, v28, v29
	v_cvt_pk_bf16_f32 v17, v30, v31
	v_cvt_pk_bf16_f32 v18, v24, v25
	v_cvt_pk_bf16_f32 v19, v26, v27
	global_store_dwordx4 v[34:35], v[16:19], off
	s_nop 1
	v_cvt_pk_bf16_f32 v16, v20, v21
	v_cvt_pk_bf16_f32 v17, v22, v23
	v_cvt_pk_bf16_f32 v18, v32, v33
	v_cvt_pk_bf16_f32 v19, v36, v37
	global_store_dwordx4 v[34:35], v[16:19], off offset:256
	s_nop 1
	s_nop 0
	v_add_u32_e32 v17, 0xb0, v128
	v_mad_i64_i32 v[18:19], s[0:1], v17, s0, v[132:133]
	v_lshl_add_u64 v[18:19], v[18:19], 0, v[134:135]
	v_readlane_b32 s0, v235, 41
	v_readlane_b32 s1, v235, 42
	s_and_b64 vcc, exec, s[0:1]
	s_nop 1
	v_mov_b32_e32 v16, v242
	v_pk_mul_f32 v[14:15], v[14:15], v[16:17] op_sel_hi:[1,0]
	v_pk_mul_f32 v[12:13], v[12:13], v[16:17] op_sel_hi:[1,0]
	v_pk_mul_f32 v[10:11], v[10:11], v[16:17] op_sel_hi:[1,0]
	v_pk_mul_f32 v[8:9], v[8:9], v[16:17] op_sel_hi:[1,0]
	v_pk_mul_f32 v[6:7], v[6:7], v[16:17] op_sel_hi:[1,0]
	v_pk_mul_f32 v[4:5], v[4:5], v[16:17] op_sel_hi:[1,0]
	v_pk_mul_f32 v[20:21], v[2:3], v[16:17] op_sel_hi:[1,0]
	v_pk_mul_f32 v[16:17], v[0:1], v[16:17] op_sel_hi:[1,0]
	v_cvt_pk_bf16_f32 v0, v12, v13
	v_cvt_pk_bf16_f32 v1, v14, v15
	v_cvt_pk_bf16_f32 v2, v8, v9
	v_cvt_pk_bf16_f32 v3, v10, v11
	global_store_dwordx4 v[18:19], v[0:3], off
	s_nop 1
	v_cvt_pk_bf16_f32 v0, v4, v5
	v_cvt_pk_bf16_f32 v1, v6, v7
	v_cvt_pk_bf16_f32 v2, v16, v17
	v_cvt_pk_bf16_f32 v3, v20, v21
	global_store_dwordx4 v[18:19], v[0:3], off offset:256
	s_waitcnt vmcnt(0)
	s_barrier
	s_waitcnt vmcnt(0)
	s_barrier
	s_cbranch_vccnz .LBB0_228
	v_mbcnt_lo_u32_b32 v0, -1, 0
	v_mbcnt_hi_u32_b32 v0, -1, v0
	s_nop 0
	v_cmp_eq_u32_e32 vcc, 0, v0
	s_and_saveexec_b64 s[0:1], vcc
	s_cbranch_execz .LBB0_227
	v_mov_b32_e32 v236, 0x3500
	s_movk_i32 s101, 0x4000
ATD0_POLL:
	global_load_dword v237, v236, s[78:79] sc1
	s_waitcnt vmcnt(0)
	v_cmp_ne_u32_e32 vcc, s100, v237
	s_cbranch_vccnz ATD0_DONE
	s_sleep 2
	s_add_i32 s101, s101, -1
	s_cmp_eq_u32 s101, 0
	s_cbranch_scc0 ATD0_POLL
ATD0_DONE:
	s_mov_b64 s[6:7], exec
	buffer_wbl2 sc1
	s_waitcnt vmcnt(0)
	s_waitcnt vmcnt(0)
	v_mbcnt_lo_u32_b32 v0, s6, 0
	s_add_u32 s4, s78, 0x3700
	v_mbcnt_hi_u32_b32 v0, s7, v0
	s_addc_u32 s5, s79, 0
	v_cmp_eq_u32_e32 vcc, 0, v0
	s_and_saveexec_b64 s[8:9], vcc
	s_cbranch_execz .LBB0_217
	s_bcnt1_i32_b64 s6, s[6:7]
	v_mov_b32_e32 v0, 0
	v_mov_b32_e32 v1, s6
	global_atomic_add v0, v1, s[4:5]

.LBB0_861:
	s_waitcnt vmcnt(0)
	v_readlane_b32 s0, v235, 41
	v_readlane_b32 s1, v235, 42
	s_and_b64 vcc, exec, s[0:1]
	s_waitcnt lgkmcnt(0)
	s_barrier
	s_mov_b32 s100, -1
	s_cbranch_vccnz .LBB0_915
	v_mbcnt_lo_u32_b32 v0, -1, 0
	v_mbcnt_hi_u32_b32 v0, -1, v0
	s_nop 0
	v_cmp_eq_u32_e32 vcc, 0, v0
	s_and_saveexec_b64 s[0:1], vcc
	s_cbranch_execz .LBB0_914
	s_add_i32 s4, 0, 0x20000
	v_mov_b32_e32 v0, s4
	s_waitcnt vmcnt(0) expcnt(0) lgkmcnt(0)
	ds_read_b32 v2, v0
	s_add_i32 s4, 0, 0x20004
	v_mov_b32_e32 v0, s4
	ds_read_b32 v0, v0
	s_waitcnt lgkmcnt(1)
	v_cmp_ne_u32_e32 vcc, 0, v2
	s_cbranch_vccnz .LBB0_878
	v_readlane_b32 s4, v235, 0
	v_readlane_b32 s5, v235, 1
	v_readlane_b32 s6, v235, 2
	s_mul_i32 s18, s5, s6
	s_mul_i32 s18, s18, s4
	s_add_u32 s4, s78, 0x1000
	s_addc_u32 s5, s79, 0
	s_add_u32 s6, s78, 0x1100
	s_addc_u32 s7, s79, 0
	s_add_u32 s8, s78, 0x1200
	s_addc_u32 s9, s79, 0
	s_add_u32 s10, s78, 0x1300
	s_addc_u32 s11, s79, 0
	s_mov_b32 s19, 1
	v_mov_b32_e32 v16, 0
	s_branch .LBB0_866

.LBB0_880:
	s_or_b64 exec, exec, s[8:9]
	v_cvt_f32_u32_e32 v4, v2
	s_waitcnt vmcnt(0)
	v_readfirstlane_b32 s6, v3
	v_sub_u32_e32 v3, 0, v2
	v_rcp_iflag_f32_e32 v4, v4
	v_add_u32_e32 v5, s6, v1
	v_mul_f32_e32 v4, 0x4f7ffffe, v4
	v_cvt_u32_f32_e32 v4, v4
	v_mul_lo_u32 v1, v3, v4
	v_mul_hi_u32 v1, v4, v1
	v_add_u32_e32 v1, v4, v1
	v_mul_hi_u32 v1, v5, v1
	v_mul_lo_u32 v3, v1, v2
	v_sub_u32_e32 v3, v5, v3
	v_add_u32_e32 v4, 1, v1
	v_cmp_ge_u32_e32 vcc, v3, v2
	s_nop 1
	v_cndmask_b32_e32 v1, v1, v4, vcc
	v_sub_u32_e32 v4, v3, v2
	v_cndmask_b32_e32 v3, v3, v4, vcc
	v_add_u32_e32 v4, 1, v1
	v_cmp_ge_u32_e32 vcc, v3, v2
	v_add_u32_e32 v3, 1, v5
	s_nop 0
	v_cndmask_b32_e32 v1, v1, v4, vcc
	v_mul_lo_u32 v4, v2, v1
	v_add_u32_e32 v2, v4, v2
	v_cmp_ne_u32_e32 vcc, v3, v2
	s_and_saveexec_b64 s[6:7], vcc
	s_xor_b64 s[6:7], exec, s[6:7]
	s_cbranch_execz .LBB0_894
	s_waitcnt lgkmcnt(0)
	v_mov_b32_e32 v0, 0x3500
	global_load_dword v0, v0, s[78:79] sc1
	s_add_u32 s10, s78, 0x3500
	s_addc_u32 s11, s79, 0
	s_waitcnt vmcnt(0)
	v_cmp_eq_u32_e32 vcc, v0, v1
	s_cmp_lt_u32 s2, 16
	s_cbranch_scc0 ATB1_24509
	v_readfirstlane_b32 s100, v1
	s_mov_b64 vcc, 0
ATB1_24509:
	s_and_saveexec_b64 s[8:9], vcc
	s_cbranch_execz .LBB0_893
	s_mov_b32 s22, 1
	s_mov_b64 s[12:13], 0
	v_mov_b32_e32 v0, 0
	s_branch .LBB0_884

.LBB0_897:
	s_or_b64 exec, exec, s[8:9]
	s_waitcnt vmcnt(0)
	v_readfirstlane_b32 s6, v2
	v_cvt_f32_u32_e32 v2, v0
	v_sub_u32_e32 v3, 0, v0
	v_add_u32_e32 v1, s6, v1
	s_add_u32 s6, s78, 0x3500
	v_rcp_iflag_f32_e32 v2, v2
	s_addc_u32 s7, s79, 0
	s_mov_b64 s[10:11], -1
	v_mul_f32_e32 v2, 0x4f7ffffe, v2
	v_cvt_u32_f32_e32 v2, v2
	v_mul_lo_u32 v3, v3, v2
	v_mul_hi_u32 v3, v2, v3
	v_add_u32_e32 v2, v2, v3
	v_mul_hi_u32 v2, v1, v2
	v_mul_lo_u32 v3, v2, v0
	v_sub_u32_e32 v3, v1, v3
	v_cmp_ge_u32_e32 vcc, v3, v0
	v_add_u32_e32 v4, 1, v2
	v_add_u32_e32 v1, 1, v1
	v_cndmask_b32_e32 v2, v2, v4, vcc
	v_sub_u32_e32 v4, v3, v0
	v_cndmask_b32_e32 v3, v3, v4, vcc
	v_cmp_ge_u32_e32 vcc, v3, v0
	v_add_u32_e32 v3, 1, v2
	s_nop 0
	v_cndmask_b32_e32 v2, v2, v3, vcc
	v_mul_lo_u32 v3, v0, v2
	v_add_u32_e32 v0, v3, v0
	v_cmp_ne_u32_e32 vcc, v1, v0
	v_mov_b64_e32 v[0:1], s[6:7]
	s_and_saveexec_b64 s[8:9], vcc
	s_cbranch_execz .LBB0_909
	v_mov_b32_e32 v0, 0
	global_load_dword v1, v0, s[6:7] sc1
	s_mov_b64 s[14:15], 0
	s_waitcnt vmcnt(0)
	v_cmp_eq_u32_e32 vcc, v1, v2
	s_cmp_lt_u32 s2, 16
	s_cbranch_scc0 ATB1_24649
	v_readfirstlane_b32 s100, v2
	s_mov_b64 vcc, 0
ATB1_24649:
	s_and_saveexec_b64 s[12:13], vcc
	s_cbranch_execz .LBB0_908
	s_add_u32 s10, s78, 0x200
	s_addc_u32 s11, s79, 0
	s_mov_b32 s24, 1
	s_branch .LBB0_901

.LBB0_922:
	v_ashrrev_i32_e32 v128, 1, v140
	v_and_b32_e32 v129, -8, v128
	v_lshl_add_u32 v128, s0, 8, v141
	s_lshl_b32 s0, s4, 8
	v_readlane_b32 s1, v235, 37
	s_or_b32 s0, s1, s0
	v_add_u32_e32 v132, s0, v129
	v_ashrrev_i32_e32 v133, 31, v132
	s_movk_i32 s0, 0x1040
	v_mov_b64_e32 v[130:131], s[52:53]
	v_ashrrev_i32_e32 v129, 31, v128
	v_mad_i64_i32 v[134:135], s[4:5], v128, s0, v[130:131]
	v_lshlrev_b64 v[132:133], 1, v[132:133]
	v_lshl_add_u64 v[136:137], v[134:135], 0, v[132:133]
	v_lshl_add_u64 v[134:135], v[128:129], 2, s[88:89]
	global_load_dword v138, v[134:135], off
	global_load_dword v236, v[134:135], off offset:64
	global_load_dword v237, v[134:135], off offset:128
	global_load_dword v238, v[134:135], off offset:192
	global_load_dword v239, v[134:135], off offset:512
	global_load_dword v240, v[134:135], off offset:576
	global_load_dword v241, v[134:135], off offset:640
	global_load_dword v242, v[134:135], off offset:704
	s_waitcnt vmcnt(0)
	v_pk_mul_f32 v[126:127], v[126:127], v[138:139] op_sel_hi:[1,0]
	v_pk_mul_f32 v[124:125], v[124:125], v[138:139] op_sel_hi:[1,0]
	v_pk_mul_f32 v[140:141], v[122:123], v[138:139] op_sel_hi:[1,0]
	v_pk_mul_f32 v[122:123], v[120:121], v[138:139] op_sel_hi:[1,0]
	v_cvt_pk_bf16_f32 v120, v124, v125
	v_cvt_pk_bf16_f32 v121, v126, v127
	v_pk_mul_f32 v[116:117], v[116:117], v[138:139] op_sel_hi:[1,0]
	v_cvt_pk_bf16_f32 v122, v122, v123
	v_cvt_pk_bf16_f32 v123, v140, v141
	global_store_dwordx4 v[136:137], v[120:123], off
	v_pk_mul_f32 v[118:119], v[118:119], v[138:139] op_sel_hi:[1,0]
	s_nop 0
	v_pk_mul_f32 v[120:121], v[114:115], v[138:139] op_sel_hi:[1,0]
	v_pk_mul_f32 v[114:115], v[112:113], v[138:139] op_sel_hi:[1,0]
	v_cvt_pk_bf16_f32 v112, v116, v117
	v_cvt_pk_bf16_f32 v113, v118, v119
	s_nop 0
	v_cvt_pk_bf16_f32 v114, v114, v115
	v_cvt_pk_bf16_f32 v115, v120, v121
	global_store_dwordx4 v[136:137], v[112:115], off offset:256
	s_nop 1
	v_or_b32_e32 v112, 16, v128
	v_ashrrev_i32_e32 v113, 31, v112
	v_mad_i64_i32 v[114:115], s[4:5], v112, s0, v[130:131]
	v_lshl_add_u64 v[112:113], v[112:113], 2, s[88:89]
	s_nop 1
	v_lshl_add_u64 v[114:115], v[114:115], 0, v[132:133]
	s_nop 1
	v_mov_b32_e32 v112, v236
	v_pk_mul_f32 v[110:111], v[110:111], v[112:113] op_sel_hi:[1,0]
	v_pk_mul_f32 v[108:109], v[108:109], v[112:113] op_sel_hi:[1,0]
	v_pk_mul_f32 v[116:117], v[106:107], v[112:113] op_sel_hi:[1,0]
	v_pk_mul_f32 v[106:107], v[104:105], v[112:113] op_sel_hi:[1,0]
	v_cvt_pk_bf16_f32 v104, v108, v109
	v_cvt_pk_bf16_f32 v105, v110, v111
	v_pk_mul_f32 v[100:101], v[100:101], v[112:113] op_sel_hi:[1,0]
	v_cvt_pk_bf16_f32 v106, v106, v107
	v_cvt_pk_bf16_f32 v107, v116, v117
	global_store_dwordx4 v[114:115], v[104:107], off
	v_pk_mul_f32 v[102:103], v[102:103], v[112:113] op_sel_hi:[1,0]
	s_nop 0
	v_pk_mul_f32 v[104:105], v[98:99], v[112:113] op_sel_hi:[1,0]
	v_pk_mul_f32 v[98:99], v[96:97], v[112:113] op_sel_hi:[1,0]
	v_cvt_pk_bf16_f32 v96, v100, v101
	v_cvt_pk_bf16_f32 v97, v102, v103
	s_nop 0
	v_cvt_pk_bf16_f32 v98, v98, v99
	v_cvt_pk_bf16_f32 v99, v104, v105
	global_store_dwordx4 v[114:115], v[96:99], off offset:256
	s_nop 1
	v_or_b32_e32 v96, 32, v128
	v_ashrrev_i32_e32 v97, 31, v96
	v_mad_i64_i32 v[98:99], s[4:5], v96, s0, v[130:131]
	v_lshl_add_u64 v[96:97], v[96:97], 2, s[88:89]
	s_nop 1
	v_lshl_add_u64 v[98:99], v[98:99], 0, v[132:133]
	s_nop 1
	v_mov_b32_e32 v96, v237
	v_pk_mul_f32 v[94:95], v[94:95], v[96:97] op_sel_hi:[1,0]
	v_pk_mul_f32 v[92:93], v[92:93], v[96:97] op_sel_hi:[1,0]
	v_pk_mul_f32 v[100:101], v[90:91], v[96:97] op_sel_hi:[1,0]
	v_pk_mul_f32 v[90:91], v[88:89], v[96:97] op_sel_hi:[1,0]
	v_cvt_pk_bf16_f32 v88, v92, v93
	v_cvt_pk_bf16_f32 v89, v94, v95
	v_pk_mul_f32 v[84:85], v[84:85], v[96:97] op_sel_hi:[1,0]
	v_cvt_pk_bf16_f32 v90, v90, v91
	v_cvt_pk_bf16_f32 v91, v100, v101
	global_store_dwordx4 v[98:99], v[88:91], off
	v_pk_mul_f32 v[86:87], v[86:87], v[96:97] op_sel_hi:[1,0]
	s_nop 0
	v_pk_mul_f32 v[88:89], v[82:83], v[96:97] op_sel_hi:[1,0]
	v_pk_mul_f32 v[82:83], v[80:81], v[96:97] op_sel_hi:[1,0]
	v_cvt_pk_bf16_f32 v80, v84, v85
	v_cvt_pk_bf16_f32 v81, v86, v87
	s_nop 0
	v_cvt_pk_bf16_f32 v82, v82, v83
	v_cvt_pk_bf16_f32 v83, v88, v89
	global_store_dwordx4 v[98:99], v[80:83], off offset:256
	s_nop 1
	v_or_b32_e32 v80, 48, v128
	v_ashrrev_i32_e32 v81, 31, v80
	v_mad_i64_i32 v[82:83], s[4:5], v80, s0, v[130:131]
	v_lshl_add_u64 v[80:81], v[80:81], 2, s[88:89]
	s_nop 1
	v_lshl_add_u64 v[82:83], v[82:83], 0, v[132:133]
	s_nop 1
	v_mov_b32_e32 v80, v238
	v_pk_mul_f32 v[78:79], v[78:79], v[80:81] op_sel_hi:[1,0]
	v_pk_mul_f32 v[76:77], v[76:77], v[80:81] op_sel_hi:[1,0]
	v_pk_mul_f32 v[84:85], v[74:75], v[80:81] op_sel_hi:[1,0]
	v_pk_mul_f32 v[74:75], v[72:73], v[80:81] op_sel_hi:[1,0]
	v_cvt_pk_bf16_f32 v72, v76, v77
	v_cvt_pk_bf16_f32 v73, v78, v79
	v_pk_mul_f32 v[70:71], v[70:71], v[80:81] op_sel_hi:[1,0]
	v_cvt_pk_bf16_f32 v74, v74, v75
	v_cvt_pk_bf16_f32 v75, v84, v85
	global_store_dwordx4 v[82:83], v[72:75], off
	v_pk_mul_f32 v[68:69], v[68:69], v[80:81] op_sel_hi:[1,0]
	s_nop 0
	v_pk_mul_f32 v[72:73], v[66:67], v[80:81] op_sel_hi:[1,0]
	v_pk_mul_f32 v[66:67], v[64:65], v[80:81] op_sel_hi:[1,0]
	v_cvt_pk_bf16_f32 v64, v68, v69
	v_cvt_pk_bf16_f32 v65, v70, v71
	s_nop 0
	v_cvt_pk_bf16_f32 v66, v66, v67
	v_cvt_pk_bf16_f32 v67, v72, v73
	global_store_dwordx4 v[82:83], v[64:67], off offset:256
	s_nop 1
	s_nop 1
	v_mov_b32_e32 v66, v239
	v_pk_mul_f32 v[62:63], v[62:63], v[66:67] op_sel_hi:[1,0]
	v_add_u32_e32 v64, 0x80, v128
	v_mad_i64_i32 v[64:65], s[4:5], v64, s0, v[130:131]
	v_lshl_add_u64 v[64:65], v[64:65], 0, v[132:133]
	v_pk_mul_f32 v[60:61], v[60:61], v[66:67] op_sel_hi:[1,0]
	v_pk_mul_f32 v[68:69], v[58:59], v[66:67] op_sel_hi:[1,0]
	v_pk_mul_f32 v[58:59], v[56:57], v[66:67] op_sel_hi:[1,0]
	v_cvt_pk_bf16_f32 v56, v60, v61
	v_cvt_pk_bf16_f32 v57, v62, v63
	v_pk_mul_f32 v[54:55], v[54:55], v[66:67] op_sel_hi:[1,0]
	v_cvt_pk_bf16_f32 v58, v58, v59
	v_cvt_pk_bf16_f32 v59, v68, v69
	global_store_dwordx4 v[64:65], v[56:59], off
	v_pk_mul_f32 v[52:53], v[52:53], v[66:67] op_sel_hi:[1,0]
	s_nop 0
	v_pk_mul_f32 v[56:57], v[50:51], v[66:67] op_sel_hi:[1,0]
	v_pk_mul_f32 v[50:51], v[48:49], v[66:67] op_sel_hi:[1,0]
	v_cvt_pk_bf16_f32 v48, v52, v53
	v_cvt_pk_bf16_f32 v49, v54, v55
	s_nop 0
	v_cvt_pk_bf16_f32 v50, v50, v51
	v_cvt_pk_bf16_f32 v51, v56, v57
	global_store_dwordx4 v[64:65], v[48:51], off offset:256
	s_nop 1
	s_nop 1
	v_mov_b32_e32 v50, v240
	v_pk_mul_f32 v[46:47], v[46:47], v[50:51] op_sel_hi:[1,0]
	v_add_u32_e32 v48, 0x90, v128
	v_mad_i64_i32 v[48:49], s[4:5], v48, s0, v[130:131]
	v_lshl_add_u64 v[48:49], v[48:49], 0, v[132:133]
	v_pk_mul_f32 v[44:45], v[44:45], v[50:51] op_sel_hi:[1,0]
	v_pk_mul_f32 v[52:53], v[42:43], v[50:51] op_sel_hi:[1,0]
	v_pk_mul_f32 v[42:43], v[40:41], v[50:51] op_sel_hi:[1,0]
	v_cvt_pk_bf16_f32 v40, v44, v45
	v_cvt_pk_bf16_f32 v41, v46, v47
	v_pk_mul_f32 v[38:39], v[38:39], v[50:51] op_sel_hi:[1,0]
	v_cvt_pk_bf16_f32 v42, v42, v43
	v_cvt_pk_bf16_f32 v43, v52, v53
	global_store_dwordx4 v[48:49], v[40:43], off
	v_pk_mul_f32 v[36:37], v[36:37], v[50:51] op_sel_hi:[1,0]
	s_nop 0
	v_pk_mul_f32 v[40:41], v[34:35], v[50:51] op_sel_hi:[1,0]
	v_pk_mul_f32 v[34:35], v[32:33], v[50:51] op_sel_hi:[1,0]
	v_cvt_pk_bf16_f32 v32, v36, v37
	v_cvt_pk_bf16_f32 v33, v38, v39
	s_nop 0
	v_cvt_pk_bf16_f32 v34, v34, v35
	v_cvt_pk_bf16_f32 v35, v40, v41
	global_store_dwordx4 v[48:49], v[32:35], off offset:256
	s_nop 1
	s_nop 1
	v_mov_b32_e32 v34, v241
	v_pk_mul_f32 v[30:31], v[30:31], v[34:35] op_sel_hi:[1,0]
	v_add_u32_e32 v32, 0xa0, v128
	v_mad_i64_i32 v[32:33], s[4:5], v32, s0, v[130:131]
	v_lshl_add_u64 v[32:33], v[32:33], 0, v[132:133]
	v_pk_mul_f32 v[28:29], v[28:29], v[34:35] op_sel_hi:[1,0]
	v_pk_mul_f32 v[36:37], v[26:27], v[34:35] op_sel_hi:[1,0]
	v_pk_mul_f32 v[26:27], v[24:25], v[34:35] op_sel_hi:[1,0]
	v_cvt_pk_bf16_f32 v24, v28, v29
	v_cvt_pk_bf16_f32 v25, v30, v31
	v_pk_mul_f32 v[22:23], v[22:23], v[34:35] op_sel_hi:[1,0]
	v_cvt_pk_bf16_f32 v26, v26, v27
	v_cvt_pk_bf16_f32 v27, v36, v37
	global_store_dwordx4 v[32:33], v[24:27], off
	v_pk_mul_f32 v[20:21], v[20:21], v[34:35] op_sel_hi:[1,0]
	s_nop 0
	v_pk_mul_f32 v[24:25], v[18:19], v[34:35] op_sel_hi:[1,0]
	v_pk_mul_f32 v[18:19], v[16:17], v[34:35] op_sel_hi:[1,0]
	v_cvt_pk_bf16_f32 v16, v20, v21
	v_cvt_pk_bf16_f32 v17, v22, v23
	s_nop 0
	v_cvt_pk_bf16_f32 v18, v18, v19
	v_cvt_pk_bf16_f32 v19, v24, v25
	global_store_dwordx4 v[32:33], v[16:19], off offset:256
	s_nop 1
	s_nop 1
	v_mov_b32_e32 v18, v242
	v_pk_mul_f32 v[14:15], v[14:15], v[18:19] op_sel_hi:[1,0]
	v_add_u32_e32 v16, 0xb0, v128
	v_mad_i64_i32 v[16:17], s[0:1], v16, s0, v[130:131]
	v_lshl_add_u64 v[16:17], v[16:17], 0, v[132:133]
	v_pk_mul_f32 v[12:13], v[12:13], v[18:19] op_sel_hi:[1,0]
	v_pk_mul_f32 v[20:21], v[10:11], v[18:19] op_sel_hi:[1,0]
	v_pk_mul_f32 v[10:11], v[8:9], v[18:19] op_sel_hi:[1,0]
	v_cvt_pk_bf16_f32 v8, v12, v13
	v_cvt_pk_bf16_f32 v9, v14, v15
	v_pk_mul_f32 v[6:7], v[6:7], v[18:19] op_sel_hi:[1,0]
	v_cvt_pk_bf16_f32 v10, v10, v11
	v_cvt_pk_bf16_f32 v11, v20, v21
	global_store_dwordx4 v[16:17], v[8:11], off
	v_pk_mul_f32 v[4:5], v[4:5], v[18:19] op_sel_hi:[1,0]
	v_readlane_b32 s0, v235, 41
	v_pk_mul_f32 v[8:9], v[2:3], v[18:19] op_sel_hi:[1,0]
	v_pk_mul_f32 v[2:3], v[0:1], v[18:19] op_sel_hi:[1,0]
	v_cvt_pk_bf16_f32 v0, v4, v5
	v_cvt_pk_bf16_f32 v1, v6, v7
	v_readlane_b32 s1, v235, 42
	v_cvt_pk_bf16_f32 v2, v2, v3
	v_cvt_pk_bf16_f32 v3, v8, v9
	global_store_dwordx4 v[16:17], v[0:3], off offset:256
	s_waitcnt vmcnt(0)
	s_barrier
	s_waitcnt vmcnt(0)
	s_and_b64 vcc, exec, s[0:1]
	s_barrier
	s_cbranch_vccnz .LBB0_936
	v_mbcnt_lo_u32_b32 v0, -1, 0
	v_mbcnt_hi_u32_b32 v0, -1, v0
	s_nop 0
	v_cmp_eq_u32_e32 vcc, 0, v0
	s_and_saveexec_b64 s[0:1], vcc
	s_cbranch_execz .LBB0_935
	v_mov_b32_e32 v236, 0x3500
	s_movk_i32 s101, 0x4000
ATD1_POLL:
	global_load_dword v237, v236, s[78:79] sc1
	s_waitcnt vmcnt(0)
	v_cmp_ne_u32_e32 vcc, s100, v237
	s_cbranch_vccnz ATD1_DONE
	s_sleep 2
	s_add_i32 s101, s101, -1
	s_cmp_eq_u32 s101, 0
	s_cbranch_scc0 ATD1_POLL
ATD1_DONE:
	s_mov_b64 s[6:7], exec
	buffer_wbl2 sc1
	s_waitcnt vmcnt(0)
	s_waitcnt vmcnt(0)
	v_mbcnt_lo_u32_b32 v0, s6, 0
	s_add_u32 s4, s78, 0x3800
	v_mbcnt_hi_u32_b32 v0, s7, v0
	s_addc_u32 s5, s79, 0
	v_cmp_eq_u32_e32 vcc, 0, v0
	s_and_saveexec_b64 s[8:9], vcc
	s_cbranch_execz .LBB0_926
	s_bcnt1_i32_b64 s6, s[6:7]
	v_mov_b32_e32 v0, 0
	v_mov_b32_e32 v1, s6
	global_atomic_add v0, v1, s[4:5]

.LBB0_1589:
	s_or_b64 exec, exec, s[8:9]
	v_cvt_f32_u32_e32 v4, v2
	s_waitcnt vmcnt(0)
	v_readfirstlane_b32 s6, v3
	v_sub_u32_e32 v3, 0, v2
	v_rcp_iflag_f32_e32 v4, v4
	v_add_u32_e32 v5, s6, v1
	v_mul_f32_e32 v4, 0x4f7ffffe, v4
	v_cvt_u32_f32_e32 v4, v4
	v_mul_lo_u32 v1, v3, v4
	v_mul_hi_u32 v1, v4, v1
	v_add_u32_e32 v1, v4, v1
	v_mul_hi_u32 v1, v5, v1
	v_mul_lo_u32 v3, v1, v2
	v_sub_u32_e32 v3, v5, v3
	v_add_u32_e32 v4, 1, v1
	v_cmp_ge_u32_e32 vcc, v3, v2
	s_nop 1
	v_cndmask_b32_e32 v1, v1, v4, vcc
	v_sub_u32_e32 v4, v3, v2
	v_cndmask_b32_e32 v3, v3, v4, vcc
	v_add_u32_e32 v4, 1, v1
	v_cmp_ge_u32_e32 vcc, v3, v2
	v_add_u32_e32 v3, 1, v5
	s_nop 0
	v_cndmask_b32_e32 v1, v1, v4, vcc
	v_mul_lo_u32 v4, v2, v1
	v_add_u32_e32 v2, v4, v2
	v_cmp_ne_u32_e32 vcc, v3, v2
	s_and_saveexec_b64 s[6:7], vcc
	s_xor_b64 s[6:7], exec, s[6:7]
	s_cbranch_execz .LBB0_1603
	s_waitcnt lgkmcnt(0)
	v_mov_b32_e32 v0, 0x3500
	global_load_dword v0, v0, s[78:79] sc1
	s_add_u32 s10, s78, 0x3500
	s_addc_u32 s11, s79, 0
	s_waitcnt vmcnt(0)
	v_cmp_eq_u32_e32 vcc, v0, v1
	s_cmp_lt_u32 s2, 16
	s_cbranch_scc0 ATB2_45117
	v_readfirstlane_b32 s100, v1
	s_mov_b64 vcc, 0
ATB2_45117:
	s_and_saveexec_b64 s[8:9], vcc
	s_cbranch_execz .LBB0_1602
	s_mov_b32 s22, 1
	s_mov_b64 s[12:13], 0
	v_mov_b32_e32 v0, 0
	s_branch .LBB0_1593

.LBB0_1606:
	s_or_b64 exec, exec, s[8:9]
	s_waitcnt vmcnt(0)
	v_readfirstlane_b32 s6, v2
	v_cvt_f32_u32_e32 v2, v0
	v_sub_u32_e32 v3, 0, v0
	v_add_u32_e32 v1, s6, v1
	s_add_u32 s6, s78, 0x3500
	v_rcp_iflag_f32_e32 v2, v2
	s_addc_u32 s7, s79, 0
	s_mov_b64 s[10:11], -1
	v_mul_f32_e32 v2, 0x4f7ffffe, v2
	v_cvt_u32_f32_e32 v2, v2
	v_mul_lo_u32 v3, v3, v2
	v_mul_hi_u32 v3, v2, v3
	v_add_u32_e32 v2, v2, v3
	v_mul_hi_u32 v2, v1, v2
	v_mul_lo_u32 v3, v2, v0
	v_sub_u32_e32 v3, v1, v3
	v_cmp_ge_u32_e32 vcc, v3, v0
	v_add_u32_e32 v4, 1, v2
	v_add_u32_e32 v1, 1, v1
	v_cndmask_b32_e32 v2, v2, v4, vcc
	v_sub_u32_e32 v4, v3, v0
	v_cndmask_b32_e32 v3, v3, v4, vcc
	v_cmp_ge_u32_e32 vcc, v3, v0
	v_add_u32_e32 v3, 1, v2
	s_nop 0
	v_cndmask_b32_e32 v2, v2, v3, vcc
	v_mul_lo_u32 v3, v0, v2
	v_add_u32_e32 v0, v3, v0
	v_cmp_ne_u32_e32 vcc, v1, v0
	v_mov_b64_e32 v[0:1], s[6:7]
	s_and_saveexec_b64 s[8:9], vcc
	s_cbranch_execz .LBB0_1618
	v_mov_b32_e32 v0, 0
	global_load_dword v1, v0, s[6:7] sc1
	s_mov_b64 s[14:15], 0
	s_waitcnt vmcnt(0)
	v_cmp_eq_u32_e32 vcc, v1, v2
	s_cmp_lt_u32 s2, 16
	s_cbranch_scc0 ATB2_45257
	v_readfirstlane_b32 s100, v2
	s_mov_b64 vcc, 0
ATB2_45257:
	s_and_saveexec_b64 s[12:13], vcc
	s_cbranch_execz .LBB0_1617
	s_add_u32 s10, s78, 0x200
	s_addc_u32 s11, s79, 0
	s_mov_b32 s24, 1
	s_branch .LBB0_1610

ATD2_POLL:
	global_load_dword v237, v236, s[78:79] sc1
	s_waitcnt vmcnt(0)
	v_cmp_ne_u32_e32 vcc, s100, v237
	s_cbranch_vccnz ATD2_DONE
	s_sleep 2
	s_add_i32 s101, s101, -1
	s_cmp_eq_u32 s101, 0
	s_cbranch_scc0 ATD2_POLL
ATD2_DONE:
	s_mov_b64 s[6:7], exec
	buffer_wbl2 sc1
	s_waitcnt vmcnt(0)
	s_waitcnt vmcnt(0)
	v_mbcnt_lo_u32_b32 v0, s6, 0
	s_add_u32 s4, s78, 0x3900
	v_mbcnt_hi_u32_b32 v0, s7, v0
	s_addc_u32 s5, s79, 0
	v_cmp_eq_u32_e32 vcc, 0, v0
	s_and_saveexec_b64 s[8:9], vcc
	s_cbranch_execz .LBB0_1635
	s_bcnt1_i32_b64 s6, s[6:7]
	v_mov_b32_e32 v0, 0
	v_mov_b32_e32 v1, s6
	global_atomic_add v0, v1, s[4:5]

.LBB0_2298:
	s_or_b64 exec, exec, s[8:9]
	v_cvt_f32_u32_e32 v4, v2
	s_waitcnt vmcnt(0)
	v_readfirstlane_b32 s6, v3
	v_sub_u32_e32 v3, 0, v2
	v_rcp_iflag_f32_e32 v4, v4
	v_add_u32_e32 v5, s6, v1
	v_mul_f32_e32 v4, 0x4f7ffffe, v4
	v_cvt_u32_f32_e32 v4, v4
	v_mul_lo_u32 v1, v3, v4
	v_mul_hi_u32 v1, v4, v1
	v_add_u32_e32 v1, v4, v1
	v_mul_hi_u32 v1, v5, v1
	v_mul_lo_u32 v3, v1, v2
	v_sub_u32_e32 v3, v5, v3
	v_add_u32_e32 v4, 1, v1
	v_cmp_ge_u32_e32 vcc, v3, v2
	s_nop 1
	v_cndmask_b32_e32 v1, v1, v4, vcc
	v_sub_u32_e32 v4, v3, v2
	v_cndmask_b32_e32 v3, v3, v4, vcc
	v_add_u32_e32 v4, 1, v1
	v_cmp_ge_u32_e32 vcc, v3, v2
	v_add_u32_e32 v3, 1, v5
	s_nop 0
	v_cndmask_b32_e32 v1, v1, v4, vcc
	v_mul_lo_u32 v4, v2, v1
	v_add_u32_e32 v2, v4, v2
	v_cmp_ne_u32_e32 vcc, v3, v2
	s_and_saveexec_b64 s[6:7], vcc
	s_xor_b64 s[6:7], exec, s[6:7]
	s_cbranch_execz .LBB0_2312
	s_waitcnt lgkmcnt(0)
	v_mov_b32_e32 v0, 0x3500
	global_load_dword v0, v0, s[78:79] sc1
	s_add_u32 s10, s78, 0x3500
	s_addc_u32 s11, s79, 0
	s_waitcnt vmcnt(0)
	v_cmp_eq_u32_e32 vcc, v0, v1
	s_cmp_lt_u32 s2, 16
	s_cbranch_scc0 ATB3_65704
	v_readfirstlane_b32 s100, v1
	s_mov_b64 vcc, 0
ATB3_65704:
	s_and_saveexec_b64 s[8:9], vcc
	s_cbranch_execz .LBB0_2311
	s_mov_b32 s22, 1
	s_mov_b64 s[12:13], 0
	v_mov_b32_e32 v0, 0
	s_branch .LBB0_2302

.LBB0_2315:
	s_or_b64 exec, exec, s[8:9]
	v_cvt_f32_u32_e32 v3, v0
	s_waitcnt vmcnt(0)
	v_readfirstlane_b32 s6, v2
	s_add_u32 s8, s78, 0x3500
	s_addc_u32 s9, s79, 0
	v_rcp_iflag_f32_e32 v3, v3
	v_add_u32_e32 v1, s6, v1
	v_add_u32_e32 v4, 1, v1
	s_mov_b64 s[10:11], -1
	v_mul_f32_e32 v2, 0x4f7ffffe, v3
	v_cvt_u32_f32_e32 v2, v2
	v_sub_u32_e32 v3, 0, v0
	v_mul_lo_u32 v3, v3, v2
	v_mul_hi_u32 v3, v2, v3
	v_add_u32_e32 v2, v2, v3
	v_mul_hi_u32 v2, v1, v2
	v_mul_lo_u32 v3, v2, v0
	v_sub_u32_e32 v1, v1, v3
	v_add_u32_e32 v5, 1, v2
	v_cmp_ge_u32_e32 vcc, v1, v0
	v_sub_u32_e32 v3, v1, v0
	s_nop 0
	v_cndmask_b32_e32 v2, v2, v5, vcc
	v_cndmask_b32_e32 v1, v1, v3, vcc
	v_add_u32_e32 v3, 1, v2
	v_cmp_ge_u32_e32 vcc, v1, v0
	s_nop 1
	v_cndmask_b32_e32 v2, v2, v3, vcc
	v_mul_lo_u32 v1, v0, v2
	v_add_u32_e32 v0, v1, v0
	v_cmp_ne_u32_e32 vcc, v4, v0
	v_mov_b64_e32 v[0:1], s[8:9]
	s_and_saveexec_b64 s[6:7], vcc
	s_cbranch_execz .LBB0_2327
	v_mov_b32_e32 v0, 0
	global_load_dword v1, v0, s[8:9] sc1
	s_mov_b64 s[14:15], 0
	s_waitcnt vmcnt(0)
	v_cmp_eq_u32_e32 vcc, v1, v2
	s_cmp_lt_u32 s2, 16
	s_cbranch_scc0 ATB3_65845
	v_readfirstlane_b32 s100, v2
	s_mov_b64 vcc, 0
ATB3_65845:
	s_and_saveexec_b64 s[12:13], vcc
	s_cbranch_execz .LBB0_2326
	s_add_u32 s10, s78, 0x200
	s_addc_u32 s11, s79, 0
	s_mov_b32 s24, 1
	s_branch .LBB0_2319

.LBB0_2340:
	v_lshl_add_u32 v128, s4, 8, v141
	v_ashrrev_i32_e32 v129, 31, v128
	v_lshl_add_u64 v[130:131], v[128:129], 2, s[88:89]
	global_load_dword v136, v[130:131], off
	global_load_dword v236, v[130:131], off offset:64
	global_load_dword v237, v[130:131], off offset:128
	global_load_dword v238, v[130:131], off offset:192
	global_load_dword v239, v[130:131], off offset:512
	global_load_dword v240, v[130:131], off offset:576
	global_load_dword v241, v[130:131], off offset:640
	global_load_dword v242, v[130:131], off offset:704
	v_ashrrev_i32_e32 v129, 1, v140
	s_lshl_b32 s1, s0, 8
	v_readlane_b32 s4, v235, 37
	v_and_b32_e32 v129, -8, v129
	s_or_b32 s1, s4, s1
	v_add_u32_e32 v134, s1, v129
	s_movk_i32 s0, 0x1040
	v_mov_b64_e32 v[132:133], s[52:53]
	v_ashrrev_i32_e32 v135, 31, v134
	v_mad_i64_i32 v[138:139], s[4:5], v128, s0, v[132:133]
	v_or_b32_e32 v140, 16, v128
	v_lshlrev_b64 v[134:135], 1, v[134:135]
	v_ashrrev_i32_e32 v141, 31, v140
	v_lshl_add_u64 v[138:139], v[138:139], 0, v[134:135]
	v_lshl_add_u64 v[142:143], v[140:141], 2, s[88:89]
	s_waitcnt vmcnt(0)
	v_pk_mul_f32 v[126:127], v[126:127], v[136:137] op_sel_hi:[1,0]
	v_pk_mul_f32 v[124:125], v[124:125], v[136:137] op_sel_hi:[1,0]
	v_pk_mul_f32 v[122:123], v[122:123], v[136:137] op_sel_hi:[1,0]
	v_pk_mul_f32 v[120:121], v[120:121], v[136:137] op_sel_hi:[1,0]
	v_pk_mul_f32 v[118:119], v[118:119], v[136:137] op_sel_hi:[1,0]
	v_pk_mul_f32 v[116:117], v[116:117], v[136:137] op_sel_hi:[1,0]
	v_pk_mul_f32 v[144:145], v[114:115], v[136:137] op_sel_hi:[1,0]
	v_pk_mul_f32 v[136:137], v[112:113], v[136:137] op_sel_hi:[1,0]
	v_cvt_pk_bf16_f32 v112, v124, v125
	v_cvt_pk_bf16_f32 v113, v126, v127
	v_cvt_pk_bf16_f32 v114, v120, v121
	v_cvt_pk_bf16_f32 v115, v122, v123
	global_store_dwordx4 v[138:139], v[112:115], off
	s_nop 1
	v_cvt_pk_bf16_f32 v112, v116, v117
	v_cvt_pk_bf16_f32 v113, v118, v119
	v_cvt_pk_bf16_f32 v114, v136, v137
	v_cvt_pk_bf16_f32 v115, v144, v145
	global_store_dwordx4 v[138:139], v[112:115], off offset:256
	s_nop 1
	v_mad_i64_i32 v[116:117], s[4:5], v140, s0, v[132:133]
	v_or_b32_e32 v114, 32, v128
	v_ashrrev_i32_e32 v115, 31, v114
	v_lshl_add_u64 v[116:117], v[116:117], 0, v[134:135]
	v_lshl_add_u64 v[118:119], v[114:115], 2, s[88:89]
	s_nop 1
	v_mov_b32_e32 v112, v236
	v_pk_mul_f32 v[110:111], v[110:111], v[112:113] op_sel_hi:[1,0]
	v_pk_mul_f32 v[108:109], v[108:109], v[112:113] op_sel_hi:[1,0]
	v_pk_mul_f32 v[106:107], v[106:107], v[112:113] op_sel_hi:[1,0]
	v_pk_mul_f32 v[104:105], v[104:105], v[112:113] op_sel_hi:[1,0]
	v_pk_mul_f32 v[102:103], v[102:103], v[112:113] op_sel_hi:[1,0]
	v_pk_mul_f32 v[100:101], v[100:101], v[112:113] op_sel_hi:[1,0]
	v_pk_mul_f32 v[120:121], v[98:99], v[112:113] op_sel_hi:[1,0]
	v_pk_mul_f32 v[112:113], v[96:97], v[112:113] op_sel_hi:[1,0]
	v_cvt_pk_bf16_f32 v96, v108, v109
	v_cvt_pk_bf16_f32 v97, v110, v111
	v_cvt_pk_bf16_f32 v98, v104, v105
	v_cvt_pk_bf16_f32 v99, v106, v107
	global_store_dwordx4 v[116:117], v[96:99], off
	s_nop 1
	v_cvt_pk_bf16_f32 v96, v100, v101
	v_cvt_pk_bf16_f32 v97, v102, v103
	v_cvt_pk_bf16_f32 v98, v112, v113
	v_cvt_pk_bf16_f32 v99, v120, v121
	global_store_dwordx4 v[116:117], v[96:99], off offset:256
	s_nop 1
	v_mad_i64_i32 v[100:101], s[4:5], v114, s0, v[132:133]
	v_or_b32_e32 v98, 48, v128
	v_ashrrev_i32_e32 v99, 31, v98
	v_lshl_add_u64 v[100:101], v[100:101], 0, v[134:135]
	v_lshl_add_u64 v[102:103], v[98:99], 2, s[88:89]
	s_nop 1
	v_mov_b32_e32 v96, v237
	v_pk_mul_f32 v[94:95], v[94:95], v[96:97] op_sel_hi:[1,0]
	v_pk_mul_f32 v[92:93], v[92:93], v[96:97] op_sel_hi:[1,0]
	v_pk_mul_f32 v[90:91], v[90:91], v[96:97] op_sel_hi:[1,0]
	v_pk_mul_f32 v[88:89], v[88:89], v[96:97] op_sel_hi:[1,0]
	v_pk_mul_f32 v[82:83], v[82:83], v[96:97] op_sel_hi:[1,0]
	v_pk_mul_f32 v[80:81], v[80:81], v[96:97] op_sel_hi:[1,0]
	v_pk_mul_f32 v[104:105], v[74:75], v[96:97] op_sel_hi:[1,0]
	v_pk_mul_f32 v[96:97], v[72:73], v[96:97] op_sel_hi:[1,0]
	v_cvt_pk_bf16_f32 v72, v92, v93
	v_cvt_pk_bf16_f32 v73, v94, v95
	v_cvt_pk_bf16_f32 v74, v88, v89
	v_cvt_pk_bf16_f32 v75, v90, v91
	global_store_dwordx4 v[100:101], v[72:75], off
	s_nop 1
	v_cvt_pk_bf16_f32 v72, v80, v81
	v_cvt_pk_bf16_f32 v73, v82, v83
	v_cvt_pk_bf16_f32 v74, v96, v97
	v_cvt_pk_bf16_f32 v75, v104, v105
	global_store_dwordx4 v[100:101], v[72:75], off offset:256
	s_nop 1
	s_nop 1
	v_mov_b32_e32 v72, v238
	v_pk_mul_f32 v[80:81], v[86:87], v[72:73] op_sel_hi:[1,0]
	v_mad_i64_i32 v[74:75], s[4:5], v98, s0, v[132:133]
	v_lshl_add_u64 v[74:75], v[74:75], 0, v[134:135]
	v_pk_mul_f32 v[82:83], v[84:85], v[72:73] op_sel_hi:[1,0]
	v_pk_mul_f32 v[78:79], v[78:79], v[72:73] op_sel_hi:[1,0]
	v_pk_mul_f32 v[76:77], v[76:77], v[72:73] op_sel_hi:[1,0]
	v_pk_mul_f32 v[70:71], v[70:71], v[72:73] op_sel_hi:[1,0]
	v_pk_mul_f32 v[68:69], v[68:69], v[72:73] op_sel_hi:[1,0]
	v_pk_mul_f32 v[84:85], v[66:67], v[72:73] op_sel_hi:[1,0]
	v_pk_mul_f32 v[72:73], v[64:65], v[72:73] op_sel_hi:[1,0]
	v_cvt_pk_bf16_f32 v64, v82, v83
	v_cvt_pk_bf16_f32 v65, v80, v81
	v_cvt_pk_bf16_f32 v66, v76, v77
	v_cvt_pk_bf16_f32 v67, v78, v79
	global_store_dwordx4 v[74:75], v[64:67], off
	s_nop 1
	v_cvt_pk_bf16_f32 v64, v68, v69
	v_cvt_pk_bf16_f32 v65, v70, v71
	v_cvt_pk_bf16_f32 v66, v72, v73
	v_cvt_pk_bf16_f32 v67, v84, v85
	global_store_dwordx4 v[74:75], v[64:67], off offset:256
	s_nop 1
	s_nop 0
	v_add_u32_e32 v65, 0x80, v128
	v_mad_i64_i32 v[66:67], s[4:5], v65, s0, v[132:133]
	v_lshl_add_u64 v[66:67], v[66:67], 0, v[134:135]
	s_nop 1
	v_mov_b32_e32 v64, v239
	v_pk_mul_f32 v[62:63], v[62:63], v[64:65] op_sel_hi:[1,0]
	v_pk_mul_f32 v[60:61], v[60:61], v[64:65] op_sel_hi:[1,0]
	v_pk_mul_f32 v[58:59], v[58:59], v[64:65] op_sel_hi:[1,0]
	v_pk_mul_f32 v[56:57], v[56:57], v[64:65] op_sel_hi:[1,0]
	v_pk_mul_f32 v[54:55], v[54:55], v[64:65] op_sel_hi:[1,0]
	v_pk_mul_f32 v[52:53], v[52:53], v[64:65] op_sel_hi:[1,0]
	v_pk_mul_f32 v[68:69], v[50:51], v[64:65] op_sel_hi:[1,0]
	v_pk_mul_f32 v[64:65], v[48:49], v[64:65] op_sel_hi:[1,0]
	v_cvt_pk_bf16_f32 v48, v60, v61
	v_cvt_pk_bf16_f32 v49, v62, v63
	v_cvt_pk_bf16_f32 v50, v56, v57
	v_cvt_pk_bf16_f32 v51, v58, v59
	global_store_dwordx4 v[66:67], v[48:51], off
	s_nop 1
	v_cvt_pk_bf16_f32 v48, v52, v53
	v_cvt_pk_bf16_f32 v49, v54, v55
	v_cvt_pk_bf16_f32 v50, v64, v65
	v_cvt_pk_bf16_f32 v51, v68, v69
	global_store_dwordx4 v[66:67], v[48:51], off offset:256
	s_nop 1
	s_nop 0
	v_add_u32_e32 v49, 0x90, v128
	v_mad_i64_i32 v[50:51], s[4:5], v49, s0, v[132:133]
	v_lshl_add_u64 v[50:51], v[50:51], 0, v[134:135]
	s_nop 1
	v_mov_b32_e32 v48, v240
	v_pk_mul_f32 v[46:47], v[46:47], v[48:49] op_sel_hi:[1,0]
	v_pk_mul_f32 v[44:45], v[44:45], v[48:49] op_sel_hi:[1,0]
	v_pk_mul_f32 v[42:43], v[42:43], v[48:49] op_sel_hi:[1,0]
	v_pk_mul_f32 v[40:41], v[40:41], v[48:49] op_sel_hi:[1,0]
	v_pk_mul_f32 v[38:39], v[38:39], v[48:49] op_sel_hi:[1,0]
	v_pk_mul_f32 v[36:37], v[36:37], v[48:49] op_sel_hi:[1,0]
	v_pk_mul_f32 v[52:53], v[34:35], v[48:49] op_sel_hi:[1,0]
	v_pk_mul_f32 v[48:49], v[32:33], v[48:49] op_sel_hi:[1,0]
	v_cvt_pk_bf16_f32 v32, v44, v45
	v_cvt_pk_bf16_f32 v33, v46, v47
	v_cvt_pk_bf16_f32 v34, v40, v41
	v_cvt_pk_bf16_f32 v35, v42, v43
	global_store_dwordx4 v[50:51], v[32:35], off
	s_nop 1
	v_cvt_pk_bf16_f32 v32, v36, v37
	v_cvt_pk_bf16_f32 v33, v38, v39
	v_cvt_pk_bf16_f32 v34, v48, v49
	v_cvt_pk_bf16_f32 v35, v52, v53
	global_store_dwordx4 v[50:51], v[32:35], off offset:256
	s_nop 1
	s_nop 0
	v_add_u32_e32 v33, 0xa0, v128
	v_mad_i64_i32 v[34:35], s[4:5], v33, s0, v[132:133]
	v_lshl_add_u64 v[34:35], v[34:35], 0, v[134:135]
	s_nop 1
	v_mov_b32_e32 v32, v241
	v_pk_mul_f32 v[30:31], v[30:31], v[32:33] op_sel_hi:[1,0]
	v_pk_mul_f32 v[28:29], v[28:29], v[32:33] op_sel_hi:[1,0]
	v_pk_mul_f32 v[26:27], v[26:27], v[32:33] op_sel_hi:[1,0]
	v_pk_mul_f32 v[24:25], v[24:25], v[32:33] op_sel_hi:[1,0]
	v_pk_mul_f32 v[22:23], v[22:23], v[32:33] op_sel_hi:[1,0]
	v_pk_mul_f32 v[20:21], v[20:21], v[32:33] op_sel_hi:[1,0]
	v_pk_mul_f32 v[36:37], v[18:19], v[32:33] op_sel_hi:[1,0]
	v_pk_mul_f32 v[32:33], v[16:17], v[32:33] op_sel_hi:[1,0]
	v_cvt_pk_bf16_f32 v16, v28, v29
	v_cvt_pk_bf16_f32 v17, v30, v31
	v_cvt_pk_bf16_f32 v18, v24, v25
	v_cvt_pk_bf16_f32 v19, v26, v27
	global_store_dwordx4 v[34:35], v[16:19], off
	s_nop 1
	v_cvt_pk_bf16_f32 v16, v20, v21
	v_cvt_pk_bf16_f32 v17, v22, v23
	v_cvt_pk_bf16_f32 v18, v32, v33
	v_cvt_pk_bf16_f32 v19, v36, v37
	global_store_dwordx4 v[34:35], v[16:19], off offset:256
	s_nop 1
	s_nop 0
	v_add_u32_e32 v17, 0xb0, v128
	v_mad_i64_i32 v[18:19], s[0:1], v17, s0, v[132:133]
	v_lshl_add_u64 v[18:19], v[18:19], 0, v[134:135]
	v_readlane_b32 s0, v235, 41
	v_readlane_b32 s1, v235, 42
	s_and_b64 vcc, exec, s[0:1]
	s_nop 1
	v_mov_b32_e32 v16, v242
	v_pk_mul_f32 v[14:15], v[14:15], v[16:17] op_sel_hi:[1,0]
	v_pk_mul_f32 v[12:13], v[12:13], v[16:17] op_sel_hi:[1,0]
	v_pk_mul_f32 v[10:11], v[10:11], v[16:17] op_sel_hi:[1,0]
	v_pk_mul_f32 v[8:9], v[8:9], v[16:17] op_sel_hi:[1,0]
	v_pk_mul_f32 v[6:7], v[6:7], v[16:17] op_sel_hi:[1,0]
	v_pk_mul_f32 v[4:5], v[4:5], v[16:17] op_sel_hi:[1,0]
	v_pk_mul_f32 v[20:21], v[2:3], v[16:17] op_sel_hi:[1,0]
	v_pk_mul_f32 v[16:17], v[0:1], v[16:17] op_sel_hi:[1,0]
	v_cvt_pk_bf16_f32 v0, v12, v13
	v_cvt_pk_bf16_f32 v1, v14, v15
	v_cvt_pk_bf16_f32 v2, v8, v9
	v_cvt_pk_bf16_f32 v3, v10, v11
	global_store_dwordx4 v[18:19], v[0:3], off
	s_nop 1
	v_cvt_pk_bf16_f32 v0, v4, v5
	v_cvt_pk_bf16_f32 v1, v6, v7
	v_cvt_pk_bf16_f32 v2, v16, v17
	v_cvt_pk_bf16_f32 v3, v20, v21
	global_store_dwordx4 v[18:19], v[0:3], off offset:256
	s_waitcnt vmcnt(0)
	s_barrier
	s_waitcnt vmcnt(0)
	s_barrier
	s_cbranch_vccnz .LBB0_2354
	v_mbcnt_lo_u32_b32 v0, -1, 0
	v_mbcnt_hi_u32_b32 v0, -1, v0
	s_nop 0
	v_cmp_eq_u32_e32 vcc, 0, v0
	s_and_saveexec_b64 s[0:1], vcc
	s_cbranch_execz .LBB0_2353
	v_mov_b32_e32 v236, 0x3500
	s_movk_i32 s101, 0x4000
ATD3_POLL:
	global_load_dword v237, v236, s[78:79] sc1
	s_waitcnt vmcnt(0)
	v_cmp_ne_u32_e32 vcc, s100, v237
	s_cbranch_vccnz ATD3_DONE
	s_sleep 2
	s_add_i32 s101, s101, -1
	s_cmp_eq_u32 s101, 0
	s_cbranch_scc0 ATD3_POLL
ATD3_DONE:
	s_mov_b64 s[6:7], exec
	buffer_wbl2 sc1
	s_waitcnt vmcnt(0)
	s_waitcnt vmcnt(0)
	v_mbcnt_lo_u32_b32 v0, s6, 0
	s_add_u32 s4, s78, 0x3a00
	v_mbcnt_hi_u32_b32 v0, s7, v0
	s_addc_u32 s5, s79, 0
	v_cmp_eq_u32_e32 vcc, 0, v0
	s_and_saveexec_b64 s[8:9], vcc
	s_cbranch_execz .LBB0_2344
	s_bcnt1_i32_b64 s6, s[6:7]
	v_mov_b32_e32 v0, 0
	v_mov_b32_e32 v1, s6
	global_atomic_add v0, v1, s[4:5]
